# k3: next-layer weight conversion rebalanced toward the 32 attention workgroups that own a single item (16 tiles each), the rest over the other 176
# speedup vs baseline: 1.0309x; 1.0054x over previous
; __device__ __forceinline__ void convert_layer(const Params& p, const Lt& lt, int l, int glo, int ghi, int c, int nc, float* tile) {
;     unsigned char* ws = p.ws;
; #pragma unroll 1
;     for (int m = 0; m < 4; ++m) {
;         const int off = m == 0 ? 0 : (m == 1 ? 608 : (m == 2 ? 864 : 1888)), n = m == 0 ? 608 : (m == 1 ? 256 : 1024);
;         const int lo = (glo > off ? glo : off) - off, hi = (ghi < off + n ? ghi : off + n) - off;
;         if (lo >= hi) continue;
;         const float* src = m == 0 ? p.in[2] + (size_t)l * DM * INC : (m == 1 ? p.in[21] + (size_t)l * DM * DM : (m == 2 ? p.in[23] + (size_t)l * DM * DFF : p.in[24] + (size_t)l * DFF * DM));
;         bf16_t* dst = (bf16_t*)(m == 0 ? ws + WS_WIN + l * SZ_WIN : (m == 1 ? ws + WS_WOUT + l * SZ_WOUT : (m == 2 ? ws + WS_WUP + l * SZ_WUP : ws + WS_WDN + l * SZ_WDN)));
;         const float* scale = m == 0 ? p.in[1] + l * DM : (m == 2 ? p.in[22] + l * DM : nullptr);
;         const int K = m == 3 ? DFF : DM, N = m == 0 ? INC : (m == 2 ? DFF : DM);
;         transpose_big(lt, src, dst, scale, K, N, lo, hi, off - glo, c, nc, tile);
; template <bool COOP>
; __global__ void __launch_bounds__(NTHREADS, 2) mega(Params p0) {
;     ...
;                     if (G == 256 && l + 1 < DEPTH && !(ph0 & 1) && b0 >= 64) convert_layer(p, lt, l + 1, 0, 864, b0 - 64, nat - 64, (float*)lds);
.LBB0_228:
	v_readlane_b32 s0, v253, 52
	v_readlane_b32 s1, v253, 53
	s_andn2_b64 vcc, exec, s[0:1]
	s_cbranch_vccnz .LBB0_259
	s_cmp_gt_i32 s60, 27
	s_cselect_b64 s[0:1], -1, 0
	s_cmpk_lt_i32 s86, 0x30
	s_cselect_b64 s[4:5], -1, 0
	s_or_b64 s[0:1], s[0:1], s[4:5]
	s_and_b64 vcc, exec, s[0:1]
	s_cbranch_vccnz .LBB0_259
	v_readlane_b32 s37, v254, 1
	s_add_i32 s37, s37, 1
	s_mov_b32 s38, 2
	s_cmpk_lt_u32 s86, 0xe0
	s_cbranch_scc1 .Lc3_heavy
	s_add_i32 s34, s86, 0xffffff20
	s_movk_i32 s35, 0x200
	s_movk_i32 s36, 0x20
	s_branch .Lconv_entry
.Lc3_heavy:
	s_add_i32 s34, s86, 0x1d0
	s_movk_i32 s35, 0x360
	s_movk_i32 s36, 0xb0
	s_branch .Lconv_entry
